# attn0 plain loop: the first four transposed V fragments of each step are read during the last QK^T MFMAs into the K buffers those MFMAs just released
# baseline (speedup 1.0000x reference)
.LBB0_309:
	s_mov_b32 s77, s74
	v_add3_u32 v215, s77, v209, v208
	v_add3_u32 v216, s77, v210, v208
	v_add3_u32 v233, s77, v211, v208
	v_add3_u32 v254, s77, v212, v208
	ds_read_b128 v[234:237], v215 offset:49152
	ds_read_b128 v[238:241], v215 offset:57344
	ds_read_b128 v[242:245], v216 offset:49152
	ds_read_b128 v[246:249], v216 offset:57344
	ds_read_b128 v[250:253], v233 offset:49152
	s_add_u32 s4, s70, 0xffffc000
	s_mov_b32 s74, s72
	s_addc_u32 s5, s71, -1
	s_add_i32 s72, s72, s42
	s_setprio 1
	s_waitcnt lgkmcnt(4)
	v_mfma_f32_32x32x16_bf16 v[112:127], v[234:237], v[188:191], 0
	ds_read_b128 v[234:237], v233 offset:57344
	v_add_f32_e32 v1, 0, v230
	v_add_f32_e32 v1, v232, v1
	v_add_f32_e32 v1, v228, v1
	v_add_f32_e32 v1, v231, v1
	v_add_f32_e32 v1, v226, v1
	s_waitcnt lgkmcnt(4)
	v_mfma_f32_32x32x16_bf16 v[96:111], v[238:241], v[188:191], 0
	ds_read_b128 v[238:241], v254 offset:49152
	v_add_f32_e32 v1, v229, v1
	v_add_f32_e32 v1, v225, v1
	v_add_f32_e32 v1, v227, v1
	v_add_f32_e32 v1, v222, v1
	v_add_f32_e32 v1, v224, v1
	s_waitcnt lgkmcnt(4)
	v_mfma_f32_32x32x16_bf16 v[112:127], v[242:245], v[184:187], v[112:127]
	ds_read_b128 v[242:245], v254 offset:57344
	s_mov_b32 s73, m0
	s_mov_b32 m0, s72
	s_nop 0
	global_load_lds_dwordx4 v197, s[4:5]
	s_mov_b32 m0, s73
	v_add_f32_e32 v1, v220, v1
	v_add_f32_e32 v1, v223, v1
	v_exp_f32_e32 v2, v128
	v_add_f32_e32 v1, v218, v1
	s_waitcnt lgkmcnt(4)
	v_mfma_f32_32x32x16_bf16 v[96:111], v[246:249], v[184:187], v[96:111]
	ds_read_b128 v[246:249], v215 offset:49280
	v_exp_f32_e32 v12, v129
	v_add_f32_e32 v1, v221, v1
	v_exp_f32_e32 v13, v130
	v_add_f32_e32 v1, v217, v1
	s_waitcnt lgkmcnt(4)
	v_mfma_f32_32x32x16_bf16 v[112:127], v[250:253], v[180:183], v[112:127]
	ds_read_b128 v[250:253], v215 offset:57472
	v_exp_f32_e32 v14, v131
	v_add_f32_e32 v1, v219, v1
	v_exp_f32_e32 v15, v132
	s_waitcnt lgkmcnt(4)
	v_mfma_f32_32x32x16_bf16 v[96:111], v[234:237], v[180:183], v[96:111]
	ds_read_b128 v[234:237], v216 offset:49280
	v_add_u32_e32 v215, s74, v206
	s_addk_i32 s72, 0x400
	s_mov_b32 s73, m0
	s_mov_b32 m0, s72
	s_nop 0
	global_load_lds_dwordx4 v198, s[4:5]
	s_mov_b32 m0, s73
	v_add_f32_e32 v1, v2, v1
	v_exp_f32_e32 v18, v133
	v_add_f32_e32 v1, v12, v1
	s_waitcnt lgkmcnt(4)
	v_mfma_f32_32x32x16_bf16 v[112:127], v[238:241], v[176:179], v[112:127]
	ds_read_b128 v[238:241], v216 offset:57472
	v_exp_f32_e32 v19, v134
	v_add_f32_e32 v1, v13, v1
	v_exp_f32_e32 v20, v135
	v_add_f32_e32 v1, v14, v1
	s_waitcnt lgkmcnt(4)
	v_mfma_f32_32x32x16_bf16 v[96:111], v[242:245], v[176:179], v[96:111]
	ds_read_b128 v[242:245], v233 offset:49280
	v_exp_f32_e32 v21, v136
	v_add_f32_e32 v1, v15, v1
	v_exp_f32_e32 v22, v137
	s_waitcnt lgkmcnt(4)
	v_mfma_f32_32x32x16_bf16 v[112:127], v[246:249], v[172:175], v[112:127]
	ds_read_b128 v[246:249], v233 offset:57472
	s_add_i32 s4, s69, s97
	s_mov_b32 s5, m0
	s_mov_b32 m0, s4
	s_nop 0
	global_load_lds_dwordx4 v199, s[56:57]
	s_mov_b32 m0, s5
	v_add_f32_e32 v1, v18, v1
	v_exp_f32_e32 v23, v138
	v_add_f32_e32 v1, v19, v1
	v_exp_f32_e32 v24, v139
	s_waitcnt lgkmcnt(4)
	v_mfma_f32_32x32x16_bf16 v[96:111], v[250:253], v[172:175], v[96:111]
	ds_read_b128 v[250:253], v254 offset:49280
	v_add_f32_e32 v1, v20, v1
	v_exp_f32_e32 v25, v140
	v_add_f32_e32 v1, v21, v1
	s_waitcnt lgkmcnt(4)
	v_mfma_f32_32x32x16_bf16 v[112:127], v[234:237], v[168:171], v[112:127]
	ds_read_b128 v[234:237], v254 offset:57472
	v_exp_f32_e32 v26, v141
	v_add_f32_e32 v1, v22, v1
	v_exp_f32_e32 v27, v142
	v_add_f32_e32 v1, v23, v1
	s_waitcnt lgkmcnt(4)
	v_mfma_f32_32x32x16_bf16 v[96:111], v[238:241], v[168:171], v[96:111]
	ds_read_b64_tr_b16 v[238:239], v215 offset:0x0
	ds_read_b64_tr_b16 v[240:241], v215 offset:0x800
	s_addk_i32 s4, 0x400
	s_mov_b32 s5, m0
	s_mov_b32 m0, s4
	s_nop 0
	global_load_lds_dwordx4 v200, s[56:57]
	s_mov_b32 m0, s5
	v_exp_f32_e32 v28, v143
	v_add_f32_e32 v1, v24, v1
	v_add_f32_e32 v1, v25, v1
	v_add_f32_e32 v1, v26, v1
	s_waitcnt lgkmcnt(5)
	v_mfma_f32_32x32x16_bf16 v[112:127], v[242:245], v[164:167], v[112:127]
	ds_read_b64_tr_b16 v[242:243], v215 offset:0x1000
	ds_read_b64_tr_b16 v[244:245], v215 offset:0x1800
	v_add_f32_e32 v1, v27, v1
	v_add_f32_e32 v1, v28, v1
	v_mov_b32_e32 v3, v1
	v_cvt_pk_bf16_f32 v4, v230, v232
	v_cvt_pk_bf16_f32 v5, v228, v231
	s_waitcnt lgkmcnt(6)
	v_mfma_f32_32x32x16_bf16 v[96:111], v[246:249], v[164:167], v[96:111]
	ds_read_b64_tr_b16 v[246:247], v215 offset:0x2000
	ds_read_b64_tr_b16 v[248:249], v215 offset:0x2800
	v_cvt_pk_bf16_f32 v6, v226, v229
	s_nop 1
	v_permlane32_swap_b32_e32 v1, v3
	v_cvt_pk_bf16_f32 v7, v225, v227
	v_cvt_pk_bf16_f32 v8, v222, v224
	v_cvt_pk_bf16_f32 v9, v220, v223
	s_waitcnt lgkmcnt(7)
	v_mfma_f32_32x32x16_bf16 v[112:127], v[250:253], v[160:163], v[112:127]
	ds_read_b64_tr_b16 v[250:251], v215 offset:0x3000
	ds_read_b64_tr_b16 v[252:253], v215 offset:0x3800
	v_cvt_pk_bf16_f32 v10, v218, v221
	v_cvt_pk_bf16_f32 v11, v217, v219
	v_cvt_pk_bf16_f32 v12, v2, v12
	v_cvt_pk_bf16_f32 v13, v13, v14
	v_cvt_pk_bf16_f32 v14, v15, v18
	s_waitcnt lgkmcnt(8)
	v_mfma_f32_32x32x16_bf16 v[96:111], v[234:237], v[160:163], v[96:111]
	v_cvt_pk_bf16_f32 v15, v19, v20
	v_cvt_pk_bf16_f32 v18, v21, v22
	v_cvt_pk_bf16_f32 v19, v23, v24
	v_cvt_pk_bf16_f32 v20, v25, v26
	v_cvt_pk_bf16_f32 v21, v27, v28
	s_setprio 0
	s_waitcnt lgkmcnt(6)
	s_nop 0
	v_mfma_f32_32x32x16_bf16 v[32:47], v[4:7], v[238:241], v[32:47]
	ds_read_b64_tr_b16 v[22:23], v215 offset:0x200
	ds_read_b64_tr_b16 v[24:25], v215 offset:0xa00
	s_waitcnt lgkmcnt(6)
	v_mfma_f32_32x32x16_bf16 v[32:47], v[8:11], v[242:245], v[32:47]
	ds_read_b64_tr_b16 v[26:27], v215 offset:0x1200
	ds_read_b64_tr_b16 v[28:29], v215 offset:0x1a00
	s_waitcnt lgkmcnt(6)
	v_mfma_f32_32x32x16_bf16 v[32:47], v[12:15], v[246:249], v[32:47]
	ds_read_b64_tr_b16 v[128:129], v215 offset:0x2200
	ds_read_b64_tr_b16 v[130:131], v215 offset:0x2a00
	s_waitcnt lgkmcnt(6)
	v_mfma_f32_32x32x16_bf16 v[32:47], v[18:21], v[250:253], v[32:47]
	ds_read_b64_tr_b16 v[132:133], v215 offset:0x3200
	ds_read_b64_tr_b16 v[134:135], v215 offset:0x3a00
	s_waitcnt lgkmcnt(6)
	v_mfma_f32_32x32x16_bf16 v[48:63], v[4:7], v[22:25], v[48:63]
	ds_read_b64_tr_b16 v[22:23], v215 offset:0x400
	ds_read_b64_tr_b16 v[24:25], v215 offset:0xc00
	s_waitcnt lgkmcnt(6)
	v_mfma_f32_32x32x16_bf16 v[48:63], v[8:11], v[26:29], v[48:63]
	ds_read_b64_tr_b16 v[26:27], v215 offset:0x1400
	ds_read_b64_tr_b16 v[28:29], v215 offset:0x1c00
	s_waitcnt lgkmcnt(6)
	v_mfma_f32_32x32x16_bf16 v[48:63], v[12:15], v[128:131], v[48:63]
	ds_read_b64_tr_b16 v[128:129], v215 offset:0x2400
	ds_read_b64_tr_b16 v[130:131], v215 offset:0x2c00
	s_waitcnt lgkmcnt(6)
	v_mfma_f32_32x32x16_bf16 v[48:63], v[18:21], v[132:135], v[48:63]
	ds_read_b64_tr_b16 v[132:133], v215 offset:0x3400
	ds_read_b64_tr_b16 v[134:135], v215 offset:0x3c00
	s_waitcnt lgkmcnt(6)
	v_mfma_f32_32x32x16_bf16 v[64:79], v[4:7], v[22:25], v[64:79]
	ds_read_b64_tr_b16 v[22:23], v215 offset:0x600
	ds_read_b64_tr_b16 v[24:25], v215 offset:0xe00
	s_waitcnt lgkmcnt(6)
	v_mfma_f32_32x32x16_bf16 v[64:79], v[8:11], v[26:29], v[64:79]
	ds_read_b64_tr_b16 v[26:27], v215 offset:0x1600
	ds_read_b64_tr_b16 v[28:29], v215 offset:0x1e00
	s_waitcnt lgkmcnt(6)
	v_mfma_f32_32x32x16_bf16 v[64:79], v[12:15], v[128:131], v[64:79]
	ds_read_b64_tr_b16 v[128:129], v215 offset:0x2600
	ds_read_b64_tr_b16 v[130:131], v215 offset:0x2e00
	s_waitcnt lgkmcnt(6)
	v_mfma_f32_32x32x16_bf16 v[64:79], v[18:21], v[132:135], v[64:79]
	ds_read_b64_tr_b16 v[132:133], v215 offset:0x3600
	ds_read_b64_tr_b16 v[134:135], v215 offset:0x3e00
	s_waitcnt lgkmcnt(6)
	v_mfma_f32_32x32x16_bf16 v[80:95], v[4:7], v[22:25], v[80:95]
	v_max_f32_e32 v2, v113, v112
	v_max3_f32 v2, v2, v114, v115
	v_max3_f32 v2, v2, v116, v117
	v_max3_f32 v2, v2, v118, v119
	v_max3_f32 v2, v2, v120, v121
	v_max3_f32 v2, v2, v122, v123
	v_max3_f32 v2, v2, v124, v125
	v_max3_f32 v2, v2, v126, v127
	s_waitcnt lgkmcnt(4)
	v_mfma_f32_32x32x16_bf16 v[80:95], v[8:11], v[26:29], v[80:95]
	v_max3_f32 v2, v2, v96, v97
	v_max3_f32 v2, v2, v98, v99
	v_max3_f32 v2, v2, v100, v101
	v_max3_f32 v2, v2, v102, v103
	v_max3_f32 v2, v2, v104, v105
	v_max3_f32 v2, v2, v106, v107
	v_max3_f32 v2, v2, v108, v109
	v_max3_f32 v2, v2, v110, v111
	s_waitcnt lgkmcnt(2)
	v_mfma_f32_32x32x16_bf16 v[80:95], v[12:15], v[128:131], v[80:95]
	v_mov_b32_e32 v4, v2
	s_nop 1
	v_permlane32_swap_b32_e32 v2, v4
	v_max_f32_e32 v2, v4, v2
	v_sub_f32_e32 v4, v2, v214
	v_cmp_ge_f32_e32 vcc, 0x42b504f3, v4
	v_max_f32_e32 v2, v214, v2
	s_waitcnt lgkmcnt(0)
	v_mfma_f32_32x32x16_bf16 v[80:95], v[18:21], v[132:135], v[80:95]
	s_cmp_eq_u64 vcc, exec
	s_cbranch_scc0 .Lattn0_slowA
	v_mov_b32_e32 v4, 1.0
	v_mov_b32_e32 v2, v214
.Lattn0_backA:
	s_waitcnt vmcnt(4) lgkmcnt(0)
	s_barrier
	v_add3_u32 v215, s69, v209, v208
	v_add3_u32 v216, s69, v210, v208
	v_add3_u32 v233, s69, v211, v208
	v_add3_u32 v254, s69, v212, v208
	ds_read_b128 v[234:237], v215 offset:49152
	ds_read_b128 v[238:241], v215 offset:57344
	ds_read_b128 v[242:245], v216 offset:49152
	ds_read_b128 v[246:249], v216 offset:57344
	ds_read_b128 v[250:253], v233 offset:49152
	v_mul_f32_e32 v5, 0xbe0293ee, v2
	v_fmamk_f32 v6, v112, 0x3e0293ee, v5
	v_fmamk_f32 v7, v113, 0x3e0293ee, v5
	v_fmamk_f32 v8, v114, 0x3e0293ee, v5
	v_fmamk_f32 v9, v115, 0x3e0293ee, v5
	v_fmamk_f32 v10, v116, 0x3e0293ee, v5
	v_fmamk_f32 v11, v117, 0x3e0293ee, v5
	v_fmamk_f32 v12, v118, 0x3e0293ee, v5
	v_fmamk_f32 v13, v119, 0x3e0293ee, v5
	v_fmamk_f32 v14, v120, 0x3e0293ee, v5
	v_fmamk_f32 v15, v121, 0x3e0293ee, v5
	v_fmamk_f32 v18, v122, 0x3e0293ee, v5
	v_fmamk_f32 v19, v123, 0x3e0293ee, v5
	v_fmamk_f32 v20, v124, 0x3e0293ee, v5
	v_fmamk_f32 v21, v125, 0x3e0293ee, v5
	v_fmamk_f32 v22, v126, 0x3e0293ee, v5
	v_fmamk_f32 v23, v127, 0x3e0293ee, v5
	v_fmamk_f32 v24, v96, 0x3e0293ee, v5
	v_fmamk_f32 v25, v97, 0x3e0293ee, v5
	v_fmamk_f32 v26, v98, 0x3e0293ee, v5
	v_fmamk_f32 v27, v99, 0x3e0293ee, v5
	v_fmamk_f32 v28, v100, 0x3e0293ee, v5
	v_fmamk_f32 v29, v101, 0x3e0293ee, v5
	v_fmamk_f32 v30, v102, 0x3e0293ee, v5
	v_fmamk_f32 v31, v103, 0x3e0293ee, v5
	v_fmamk_f32 v128, v104, 0x3e0293ee, v5
	v_fmamk_f32 v129, v105, 0x3e0293ee, v5
	v_fmamk_f32 v130, v106, 0x3e0293ee, v5
	v_fmamk_f32 v131, v107, 0x3e0293ee, v5
	v_fmamk_f32 v132, v108, 0x3e0293ee, v5
	v_fmamk_f32 v133, v109, 0x3e0293ee, v5
	v_fmamk_f32 v134, v110, 0x3e0293ee, v5
	v_fmac_f32_e32 v5, 0x3e0293ee, v111
	s_setprio 1
	s_waitcnt lgkmcnt(4)
	v_mfma_f32_32x32x16_bf16 v[112:127], v[234:237], v[188:191], 0
	ds_read_b128 v[234:237], v233 offset:57344
	v_exp_f32_e32 v135, v6
	v_exp_f32_e32 v136, v7
	v_exp_f32_e32 v137, v8
	v_exp_f32_e32 v138, v9
	s_waitcnt lgkmcnt(4)
	v_mfma_f32_32x32x16_bf16 v[96:111], v[238:241], v[188:191], 0
	ds_read_b128 v[238:241], v254 offset:49152
	v_exp_f32_e32 v10, v10
	v_exp_f32_e32 v11, v11
	v_exp_f32_e32 v12, v12
	s_waitcnt lgkmcnt(4)
	v_mfma_f32_32x32x16_bf16 v[112:127], v[242:245], v[184:187], v[112:127]
	ds_read_b128 v[242:245], v254 offset:57344
	s_add_i32 s4, s77, s42
	s_mov_b32 s5, m0
	s_mov_b32 m0, s4
	s_nop 0
	global_load_lds_dwordx4 v197, s[70:71]
	s_mov_b32 m0, s5
	v_exp_f32_e32 v13, v13
	v_exp_f32_e32 v14, v14
	v_exp_f32_e32 v15, v15
	v_exp_f32_e32 v18, v18
	s_waitcnt lgkmcnt(4)
	v_mfma_f32_32x32x16_bf16 v[96:111], v[246:249], v[184:187], v[96:111]
	ds_read_b128 v[246:249], v215 offset:49280
	v_exp_f32_e32 v19, v19
	v_exp_f32_e32 v20, v20
	v_exp_f32_e32 v21, v21
	s_waitcnt lgkmcnt(4)
	v_mfma_f32_32x32x16_bf16 v[112:127], v[250:253], v[180:183], v[112:127]
	ds_read_b128 v[250:253], v215 offset:57472
	v_exp_f32_e32 v22, v22
	v_exp_f32_e32 v23, v23
	v_exp_f32_e32 v7, v24
	v_exp_f32_e32 v24, v25
	s_waitcnt lgkmcnt(4)
	v_mfma_f32_32x32x16_bf16 v[96:111], v[234:237], v[180:183], v[96:111]
	ds_read_b128 v[234:237], v216 offset:49280
	v_add_u32_e32 v215, s77, v206
	s_addk_i32 s4, 0x400
	s_mov_b32 s5, m0
	s_mov_b32 m0, s4
	s_nop 0
	global_load_lds_dwordx4 v198, s[70:71]
	s_mov_b32 m0, s5
	v_exp_f32_e32 v25, v26
	v_exp_f32_e32 v26, v27
	v_exp_f32_e32 v27, v28
	s_waitcnt lgkmcnt(4)
	v_mfma_f32_32x32x16_bf16 v[112:127], v[238:241], v[176:179], v[112:127]
	ds_read_b128 v[238:241], v216 offset:57472
	v_exp_f32_e32 v28, v29
	v_exp_f32_e32 v29, v30
	v_exp_f32_e32 v30, v31
	v_exp_f32_e32 v31, v128
	s_waitcnt lgkmcnt(4)
	v_mfma_f32_32x32x16_bf16 v[96:111], v[242:245], v[176:179], v[96:111]
	ds_read_b128 v[242:245], v233 offset:49280
	v_exp_f32_e32 v128, v129
	v_exp_f32_e32 v129, v130
	v_exp_f32_e32 v130, v131
	v_exp_f32_e32 v131, v132
	s_waitcnt lgkmcnt(4)
	v_mfma_f32_32x32x16_bf16 v[112:127], v[246:249], v[172:175], v[112:127]
	ds_read_b128 v[246:249], v233 offset:57472
	s_add_u32 s4, s56, 0x4000
	s_addc_u32 s5, s57, 0
	s_add_i32 s72, s74, s97
	s_mov_b32 s73, m0
	s_mov_b32 m0, s72
	s_nop 0
	global_load_lds_dwordx4 v199, s[4:5]
	s_mov_b32 m0, s73
	v_exp_f32_e32 v132, v133
	v_exp_f32_e32 v133, v134
	v_exp_f32_e32 v134, v5
	s_waitcnt lgkmcnt(4)
	v_mfma_f32_32x32x16_bf16 v[96:111], v[250:253], v[172:175], v[96:111]
	ds_read_b128 v[250:253], v254 offset:49280
	v_add_f32_e32 v5, 0, v135
	v_add_f32_e32 v5, v136, v5
	v_add_f32_e32 v5, v137, v5
	v_add_f32_e32 v5, v138, v5
	v_add_f32_e32 v5, v10, v5
	v_add_f32_e32 v5, v11, v5
	v_add_f32_e32 v5, v12, v5
	v_add_f32_e32 v5, v13, v5
	s_waitcnt lgkmcnt(4)
	v_mfma_f32_32x32x16_bf16 v[112:127], v[234:237], v[168:171], v[112:127]
	ds_read_b128 v[234:237], v254 offset:57472
	v_add_f32_e32 v5, v14, v5
	v_add_f32_e32 v5, v15, v5
	v_add_f32_e32 v5, v18, v5
	v_add_f32_e32 v5, v19, v5
	v_add_f32_e32 v5, v20, v5
	v_add_f32_e32 v5, v21, v5
	v_add_f32_e32 v5, v22, v5
	s_waitcnt lgkmcnt(4)
	v_mfma_f32_32x32x16_bf16 v[96:111], v[238:241], v[168:171], v[96:111]
	ds_read_b64_tr_b16 v[238:239], v215 offset:0x0
	ds_read_b64_tr_b16 v[240:241], v215 offset:0x800
	s_addk_i32 s72, 0x400
	s_mov_b32 s73, m0
	s_mov_b32 m0, s72
	s_nop 0
	global_load_lds_dwordx4 v200, s[4:5]
	s_mov_b32 m0, s73
	v_add_f32_e32 v5, v23, v5
	v_add_f32_e32 v5, v7, v5
	v_add_f32_e32 v5, v24, v5
	v_add_f32_e32 v5, v25, v5
	v_add_f32_e32 v5, v26, v5
	v_add_f32_e32 v5, v27, v5
	v_add_f32_e32 v5, v28, v5
	s_waitcnt lgkmcnt(5)
	v_mfma_f32_32x32x16_bf16 v[112:127], v[242:245], v[164:167], v[112:127]
	ds_read_b64_tr_b16 v[242:243], v215 offset:0x1000
	ds_read_b64_tr_b16 v[244:245], v215 offset:0x1800
	v_add_f32_e32 v5, v29, v5
	v_add_f32_e32 v5, v30, v5
	v_add_f32_e32 v5, v31, v5
	v_add_f32_e32 v5, v128, v5
	v_add_f32_e32 v5, v129, v5
	v_add_f32_e32 v5, v130, v5
	v_add_f32_e32 v5, v131, v5
	s_waitcnt lgkmcnt(6)
	v_mfma_f32_32x32x16_bf16 v[96:111], v[246:249], v[164:167], v[96:111]
	ds_read_b64_tr_b16 v[246:247], v215 offset:0x2000
	ds_read_b64_tr_b16 v[248:249], v215 offset:0x2800
	v_add_f32_e32 v5, v132, v5
	v_add_f32_e32 v5, v133, v5
	v_add_f32_e32 v5, v134, v5
	v_mov_b32_e32 v6, v5
	v_cvt_pk_bf16_f32 v8, v135, v136
	v_cvt_pk_bf16_f32 v9, v137, v138
	v_cvt_pk_bf16_f32 v10, v10, v11
	s_waitcnt lgkmcnt(7)
	v_mfma_f32_32x32x16_bf16 v[112:127], v[250:253], v[160:163], v[112:127]
	ds_read_b64_tr_b16 v[250:251], v215 offset:0x3000
	ds_read_b64_tr_b16 v[252:253], v215 offset:0x3800
	s_nop 1
	v_permlane32_swap_b32_e32 v5, v6
	v_cvt_pk_bf16_f32 v11, v12, v13
	v_cvt_pk_bf16_f32 v12, v14, v15
	v_cvt_pk_bf16_f32 v13, v18, v19
	v_cvt_pk_bf16_f32 v14, v20, v21
	v_cvt_pk_bf16_f32 v15, v22, v23
	v_cvt_pk_bf16_f32 v18, v7, v24
	s_waitcnt lgkmcnt(8)
	v_mfma_f32_32x32x16_bf16 v[96:111], v[234:237], v[160:163], v[96:111]
	v_cvt_pk_bf16_f32 v19, v25, v26
	v_cvt_pk_bf16_f32 v20, v27, v28
	v_cvt_pk_bf16_f32 v21, v29, v30
	v_cvt_pk_bf16_f32 v22, v31, v128
	v_cvt_pk_bf16_f32 v23, v129, v130
	v_cvt_pk_bf16_f32 v24, v131, v132
	v_cvt_pk_bf16_f32 v25, v133, v134
	s_setprio 0
	s_waitcnt lgkmcnt(6)
	s_nop 0
	v_mfma_f32_32x32x16_bf16 v[32:47], v[8:11], v[238:241], v[32:47]
	ds_read_b64_tr_b16 v[26:27], v215 offset:0x200
	ds_read_b64_tr_b16 v[28:29], v215 offset:0xa00
	s_waitcnt lgkmcnt(6)
	v_mfma_f32_32x32x16_bf16 v[32:47], v[12:15], v[242:245], v[32:47]
	ds_read_b64_tr_b16 v[128:129], v215 offset:0x1200
	ds_read_b64_tr_b16 v[130:131], v215 offset:0x1a00
	s_waitcnt lgkmcnt(6)
	v_mfma_f32_32x32x16_bf16 v[32:47], v[18:21], v[246:249], v[32:47]
	ds_read_b64_tr_b16 v[132:133], v215 offset:0x2200
	ds_read_b64_tr_b16 v[134:135], v215 offset:0x2a00
	s_waitcnt lgkmcnt(6)
	v_mfma_f32_32x32x16_bf16 v[32:47], v[22:25], v[250:253], v[32:47]
	ds_read_b64_tr_b16 v[136:137], v215 offset:0x3200
	ds_read_b64_tr_b16 v[138:139], v215 offset:0x3a00
	s_waitcnt lgkmcnt(6)
	v_mfma_f32_32x32x16_bf16 v[48:63], v[8:11], v[26:29], v[48:63]
	ds_read_b64_tr_b16 v[26:27], v215 offset:0x400
	ds_read_b64_tr_b16 v[28:29], v215 offset:0xc00
	s_waitcnt lgkmcnt(6)
	v_mfma_f32_32x32x16_bf16 v[48:63], v[12:15], v[128:131], v[48:63]
	ds_read_b64_tr_b16 v[128:129], v215 offset:0x1400
	ds_read_b64_tr_b16 v[130:131], v215 offset:0x1c00
	s_waitcnt lgkmcnt(6)
	v_mfma_f32_32x32x16_bf16 v[48:63], v[18:21], v[132:135], v[48:63]
	ds_read_b64_tr_b16 v[132:133], v215 offset:0x2400
	ds_read_b64_tr_b16 v[134:135], v215 offset:0x2c00
	s_waitcnt lgkmcnt(6)
	v_mfma_f32_32x32x16_bf16 v[48:63], v[22:25], v[136:139], v[48:63]
	ds_read_b64_tr_b16 v[136:137], v215 offset:0x3400
	ds_read_b64_tr_b16 v[138:139], v215 offset:0x3c00
	s_waitcnt lgkmcnt(6)
	v_mfma_f32_32x32x16_bf16 v[64:79], v[8:11], v[26:29], v[64:79]
	ds_read_b64_tr_b16 v[26:27], v215 offset:0x600
	ds_read_b64_tr_b16 v[28:29], v215 offset:0xe00
	s_waitcnt lgkmcnt(6)
	v_mfma_f32_32x32x16_bf16 v[64:79], v[12:15], v[128:131], v[64:79]
	ds_read_b64_tr_b16 v[128:129], v215 offset:0x1600
	ds_read_b64_tr_b16 v[130:131], v215 offset:0x1e00
	s_waitcnt lgkmcnt(6)
	v_mfma_f32_32x32x16_bf16 v[64:79], v[18:21], v[132:135], v[64:79]
	ds_read_b64_tr_b16 v[132:133], v215 offset:0x2600
	ds_read_b64_tr_b16 v[134:135], v215 offset:0x2e00
	s_waitcnt lgkmcnt(6)
	v_mfma_f32_32x32x16_bf16 v[64:79], v[22:25], v[136:139], v[64:79]
	ds_read_b64_tr_b16 v[136:137], v215 offset:0x3600
	ds_read_b64_tr_b16 v[138:139], v215 offset:0x3e00
	s_waitcnt lgkmcnt(6)
	v_mfma_f32_32x32x16_bf16 v[80:95], v[8:11], v[26:29], v[80:95]
	v_max_f32_e32 v7, v113, v112
	v_max3_f32 v7, v7, v114, v115
	v_max3_f32 v7, v7, v116, v117
	v_max3_f32 v7, v7, v118, v119
	v_max3_f32 v7, v7, v120, v121
	v_max3_f32 v7, v7, v122, v123
	v_max3_f32 v7, v7, v124, v125
	v_max3_f32 v7, v7, v126, v127
	s_waitcnt lgkmcnt(4)
	v_mfma_f32_32x32x16_bf16 v[80:95], v[12:15], v[128:131], v[80:95]
	v_max3_f32 v7, v7, v96, v97
	v_max3_f32 v7, v7, v98, v99
	v_max3_f32 v7, v7, v100, v101
	v_max3_f32 v7, v7, v102, v103
	v_max3_f32 v7, v7, v104, v105
	v_max3_f32 v7, v7, v106, v107
	v_max3_f32 v7, v7, v108, v109
	v_max3_f32 v7, v7, v110, v111
	s_waitcnt lgkmcnt(2)
	v_mfma_f32_32x32x16_bf16 v[80:95], v[18:21], v[132:135], v[80:95]
	v_mov_b32_e32 v8, v7
	s_nop 1
	v_permlane32_swap_b32_e32 v7, v8
	v_max_f32_e32 v7, v8, v7
	v_sub_f32_e32 v8, v7, v2
	v_cmp_ge_f32_e32 vcc, 0x42b504f3, v8
	v_max_f32_e32 v8, v2, v7
	s_waitcnt lgkmcnt(0)
	v_mfma_f32_32x32x16_bf16 v[80:95], v[22:25], v[136:139], v[80:95]
	s_cmp_eq_u64 vcc, exec
	s_cbranch_scc0 .Lattn0_slowB
	v_mov_b32_e32 v7, 1.0
	v_mov_b32_e32 v214, v2
